# v69 + 7.12: rescale-branch test shortened to one v_cmp against a per-tile threshold SGPR (-inf on the first tile), first-tile mask computed only on the rare path
# speedup vs baseline: 1.0037x; 1.0037x over previous
; #define MFMA32(a, b, c) __builtin_amdgcn_mfma_f32_32x32x16_bf16((a), (b), (c), 0, 0, 0)
; template <int DQK, int KROW, bool BIAS, bool MAPS2>
; DI void attn_core(const int t, const u16* __restrict__ Q, int ldq, const u16* __restrict__ Kp, int ldk, const u16* __restrict__ Vt, int q0,
;                   char* lds, const float* lut, float b31, f32x16 (&o)[4], float& l_out) {
;     ...
;     const bool live = (kt << 6) <= wq0 + 31;
;     if (live) {
;       const int k0 = kt << 6;
;       const bool far = BIAS && (wq0 - (k0 + 63) >= 128);
;       const float init = (far ? b31 : 0.f) - m_run;
; #pragma unroll
;       for (int k2 = 0; k2 < 2; ++k2)
; #pragma unroll
;         for (int i = 0; i < 16; ++i) s[k2][i] = init;
;       {
;         constexpr int QBS = (NKS > 4) ? 2 : 4, NBT = NKS / QBS;
;         bf16x8 kfb[2][QBS][2];
;         const char* kbase = lds + (kt & 1) * AT_KBUF + r * KS + hf * 16 + map * (DQK * 2);
; #pragma unroll
;         for (int jq = 0; jq < QBS; ++jq)
; #pragma unroll
;           for (int k2 = 0; k2 < 2; ++k2) kfb[0][jq][k2] = *(const bf16x8*)(kbase + 32 * k2 * KS + jq * 32);
; #pragma unroll
;         for (int b = 0; b < NBT; ++b) {
;           if (b + 1 < NBT) {
; #pragma unroll
;             for (int jq = 0; jq < QBS; ++jq)
; #pragma unroll
;               for (int k2 = 0; k2 < 2; ++k2) kfb[(b + 1) & 1][jq][k2] = *(const bf16x8*)(kbase + 32 * k2 * KS + ((b + 1) * QBS + jq) * 32);
;           }
;           __builtin_amdgcn_sched_barrier(0);
;           __builtin_amdgcn_s_setprio(1);
; #pragma unroll
;           for (int jq = 0; jq < QBS; ++jq)
; #pragma unroll
;             for (int k2 = 0; k2 < 2; ++k2) s[k2] = MFMA32(kfb[b & 1][jq][k2], qf[b * QBS + jq], s[k2]);
;           __builtin_amdgcn_s_setprio(0);
;           __builtin_amdgcn_sched_barrier(0);
;         }
;       }
;       if (BIAS && !far) {
; #pragma unroll
;         for (int k2 = 0; k2 < 2; ++k2)
; #pragma unroll
;           for (int i = 0; i < 16; ++i) {
;             const int key = k0 + 32 * k2 + (i & 3) + 8 * (i >> 2) + 4 * hf;
;             int d = qrow - key; d = d < 0 ? 0 : (d > 128 ? 128 : d);
;             s[k2][i] += lut[d];
;           }
;       }
;     ...
;       if (__builtin_amdgcn_ballot_w64(kt == 0 || mx > RESCALE_THR)) {
.LBB0_235:
	v_cmp_le_i32_e32 vcc, s90, v155
	s_and_saveexec_b64 s[92:93], vcc
	s_cbranch_execz .LBB0_243
	s_cmp_eq_u32 s96, 0
	s_cselect_b32 s97, 0xff800000, s6
	s_movk_i32 s0, 0x80
	v_cmp_gt_i32_e32 vcc, s0, v159
	s_movk_i32 s0, 0x7f
	v_cmp_lt_i32_e64 s[0:1], s0, v159
	s_and_b32 s91, s96, 1
	s_nop 0
	v_cndmask_b32_e64 v0, 0, v152, s[0:1]
	s_mul_i32 s0, s91, 0x6400
	v_sub_f32_e32 v80, v0, v161
	v_add_u32_e32 v0, s0, v156
	ds_read_b128 v[2:5], v0 offset:8704
	ds_read_b128 v[6:9], v0
	ds_read_b128 v[10:13], v0 offset:32
	ds_read_b128 v[162:165], v0 offset:8736
	ds_read_b128 v[166:169], v0 offset:64
	ds_read_b128 v[170:173], v0 offset:8768
	ds_read_b128 v[174:177], v0 offset:96
	ds_read_b128 v[178:181], v0 offset:8800
	s_setprio 1
	v_mov_b32_e32 v81, v80
	v_mov_b32_e32 v82, v80
	v_mov_b32_e32 v83, v80
	v_mov_b32_e32 v84, v80
	v_mov_b32_e32 v85, v80
	v_mov_b32_e32 v86, v80
	v_mov_b32_e32 v87, v80
	v_mov_b32_e32 v88, v80
	v_mov_b32_e32 v89, v80
	v_mov_b32_e32 v90, v80
	v_mov_b32_e32 v91, v80
	v_mov_b32_e32 v92, v80
	v_mov_b32_e32 v93, v80
	v_mov_b32_e32 v94, v80
	v_mov_b32_e32 v95, v80
	s_waitcnt lgkmcnt(6)
	s_nop 0
	v_mfma_f32_32x32x16_bf16 v[96:111], v[6:9], v[112:115], v[80:95]
	v_mfma_f32_32x32x16_bf16 v[80:95], v[2:5], v[112:115], v[80:95]
	s_waitcnt lgkmcnt(5)
	v_mfma_f32_32x32x16_bf16 v[96:111], v[10:13], v[116:119], v[96:111]
	s_waitcnt lgkmcnt(4)
	v_mfma_f32_32x32x16_bf16 v[80:95], v[162:165], v[116:119], v[80:95]
	s_waitcnt lgkmcnt(3)
	v_mfma_f32_32x32x16_bf16 v[96:111], v[166:169], v[120:123], v[96:111]
	s_waitcnt lgkmcnt(2)
	v_mfma_f32_32x32x16_bf16 v[80:95], v[170:173], v[120:123], v[80:95]
	s_waitcnt lgkmcnt(1)
	v_mfma_f32_32x32x16_bf16 v[96:111], v[174:177], v[124:127], v[96:111]
	s_waitcnt lgkmcnt(0)
	v_mfma_f32_32x32x16_bf16 v[80:95], v[178:181], v[124:127], v[80:95]
	s_setprio 0
	s_and_saveexec_b64 s[0:1], vcc
	s_cbranch_execz .LBB0_238
	v_add_u32_e32 v0, v160, v159
	v_lshlrev_b32_e32 v0, 2, v0
	v_add_u32_e32 v0, 0x16178, v0
	ds_read2_b32 v[2:3], v0 offset0:63 offset1:62
	ds_read2_b32 v[4:5], v0 offset0:61 offset1:60
	ds_read2_b32 v[6:7], v0 offset0:55 offset1:54
	ds_read2_b32 v[8:9], v0 offset0:53 offset1:52
	ds_read2_b32 v[10:11], v0 offset0:47 offset1:46
	ds_read2_b32 v[12:13], v0 offset0:45 offset1:44
	ds_read2_b32 v[14:15], v0 offset0:39 offset1:38
	ds_read2_b32 v[162:163], v0 offset0:37 offset1:36
	ds_read2_b32 v[164:165], v0 offset0:31 offset1:30
	ds_read2_b32 v[166:167], v0 offset0:29 offset1:28
	ds_read2_b32 v[168:169], v0 offset0:23 offset1:22
	ds_read2_b32 v[170:171], v0 offset0:21 offset1:20
	ds_read2_b32 v[172:173], v0 offset0:15 offset1:14
	ds_read2_b32 v[174:175], v0 offset0:13 offset1:12
	ds_read2_b32 v[176:177], v0 offset0:7 offset1:6
	ds_read2_b32 v[178:179], v0 offset0:5 offset1:4
	s_waitcnt lgkmcnt(8)
	v_pk_add_f32 v[108:109], v[108:109], v[14:15]
	v_pk_add_f32 v[110:111], v[110:111], v[162:163]
	v_pk_add_f32 v[106:107], v[106:107], v[12:13]
	v_pk_add_f32 v[104:105], v[104:105], v[10:11]
	v_pk_add_f32 v[102:103], v[102:103], v[8:9]
	v_pk_add_f32 v[100:101], v[100:101], v[6:7]
	v_pk_add_f32 v[98:99], v[98:99], v[4:5]
	v_pk_add_f32 v[96:97], v[96:97], v[2:3]
	s_waitcnt lgkmcnt(0)
	v_pk_add_f32 v[94:95], v[94:95], v[178:179]
	v_pk_add_f32 v[92:93], v[92:93], v[176:177]
	v_pk_add_f32 v[90:91], v[90:91], v[174:175]
	v_pk_add_f32 v[88:89], v[88:89], v[172:173]
	v_pk_add_f32 v[86:87], v[86:87], v[170:171]
	v_pk_add_f32 v[84:85], v[84:85], v[168:169]
	v_pk_add_f32 v[82:83], v[82:83], v[166:167]
	v_pk_add_f32 v[80:81], v[80:81], v[164:165]
; template <int DQK, int KROW, bool BIAS, bool MAPS2>
; DI void attn_core(const int t, const u16* __restrict__ Q, int ldq, const u16* __restrict__ Kp, int ldk, const u16* __restrict__ Vt, int q0,
;                   char* lds, const float* lut, float b31, f32x16 (&o)[4], float& l_out) {
;     ...
;       float mx = s[0][0];
; #pragma unroll
;       for (int k2 = 0; k2 < 2; ++k2)
; #pragma unroll
;         for (int i = 0; i < 16; ++i) mx = fmaxf(mx, s[k2][i]);
;       mx = xhalf_max(mx);
;       if (__builtin_amdgcn_ballot_w64(kt == 0 || mx > RESCALE_THR)) {
;         const float delta = (kt == 0) ? mx : fmaxf(mx, 0.f);
;         const float alpha = __builtin_amdgcn_exp2f(-delta);
;         m_run += delta;
;         l_run *= alpha;
; #pragma unroll
;         for (int dt = 0; dt < 4; ++dt)
; #pragma unroll
;           for (int i = 0; i < 16; ++i) o[dt][i] *= alpha;
; #pragma unroll
;         for (int k2 = 0; k2 < 2; ++k2)
; #pragma unroll
;           for (int i = 0; i < 16; ++i) s[k2][i] -= delta;
;       }
.LBB0_238:
	s_or_b64 exec, exec, s[0:1]
	s_nop 4
	s_nop 0
	v_max_f32_e32 v0, v97, v97
	v_max_f32_e32 v2, v96, v96
	v_max_f32_e32 v0, v2, v0
	v_max3_f32 v0, v0, v98, v99
	v_max3_f32 v0, v0, v100, v101
	v_max3_f32 v0, v0, v102, v103
	v_max3_f32 v0, v0, v104, v105
	v_max3_f32 v0, v0, v106, v107
	v_max3_f32 v0, v0, v108, v109
	v_max3_f32 v0, v0, v110, v111
	v_max3_f32 v0, v0, v80, v81
	v_max3_f32 v0, v0, v82, v83
	v_max3_f32 v0, v0, v84, v85
	v_max3_f32 v0, v0, v86, v87
	v_max3_f32 v0, v0, v88, v89
	v_max3_f32 v0, v0, v90, v91
	v_max3_f32 v0, v0, v92, v93
	v_max3_f32 v0, v0, v94, v95
	v_mov_b32_e32 v2, v0
	s_nop 1
	v_permlane32_swap_b32_e32 v0, v2
	v_max_f32_e32 v0, v0, v2
	v_cmp_lt_f32_e32 vcc, s97, v0
	s_cbranch_vccz .LBB0_242
	s_cmp_eq_u32 s96, 0
	s_cselect_b64 s[0:1], -1, 0
	v_max_f32_e32 v2, v0, v0
	v_max_f32_e32 v2, 0, v2
	v_cndmask_b32_e64 v0, v2, v0, s[0:1]
	v_exp_f32_e64 v2, -v0
	v_add_f32_e32 v161, v161, v0
	v_pk_add_f32 v[96:97], v[96:97], v[0:1] op_sel_hi:[1,0] neg_lo:[0,1] neg_hi:[0,1]
	v_pk_add_f32 v[98:99], v[98:99], v[0:1] op_sel_hi:[1,0] neg_lo:[0,1] neg_hi:[0,1]
	v_pk_mul_f32 v[78:79], v[78:79], v[2:3] op_sel_hi:[1,0]
	v_pk_mul_f32 v[76:77], v[76:77], v[2:3] op_sel_hi:[1,0]
	v_pk_mul_f32 v[74:75], v[74:75], v[2:3] op_sel_hi:[1,0]
	v_pk_mul_f32 v[72:73], v[72:73], v[2:3] op_sel_hi:[1,0]
	v_pk_mul_f32 v[70:71], v[70:71], v[2:3] op_sel_hi:[1,0]
	v_pk_mul_f32 v[68:69], v[68:69], v[2:3] op_sel_hi:[1,0]
	v_pk_mul_f32 v[66:67], v[66:67], v[2:3] op_sel_hi:[1,0]
	v_pk_mul_f32 v[64:65], v[64:65], v[2:3] op_sel_hi:[1,0]
	v_pk_mul_f32 v[62:63], v[62:63], v[2:3] op_sel_hi:[1,0]
	v_pk_mul_f32 v[60:61], v[60:61], v[2:3] op_sel_hi:[1,0]
	v_pk_mul_f32 v[58:59], v[58:59], v[2:3] op_sel_hi:[1,0]
	v_pk_mul_f32 v[56:57], v[56:57], v[2:3] op_sel_hi:[1,0]
	v_pk_mul_f32 v[54:55], v[54:55], v[2:3] op_sel_hi:[1,0]
	v_pk_mul_f32 v[52:53], v[52:53], v[2:3] op_sel_hi:[1,0]
	v_pk_mul_f32 v[50:51], v[50:51], v[2:3] op_sel_hi:[1,0]
	v_pk_mul_f32 v[48:49], v[48:49], v[2:3] op_sel_hi:[1,0]
	v_pk_mul_f32 v[46:47], v[46:47], v[2:3] op_sel_hi:[1,0]
	v_pk_mul_f32 v[44:45], v[44:45], v[2:3] op_sel_hi:[1,0]
	v_pk_mul_f32 v[42:43], v[42:43], v[2:3] op_sel_hi:[1,0]
	v_pk_mul_f32 v[40:41], v[40:41], v[2:3] op_sel_hi:[1,0]
	v_pk_mul_f32 v[38:39], v[38:39], v[2:3] op_sel_hi:[1,0]
	v_pk_mul_f32 v[36:37], v[36:37], v[2:3] op_sel_hi:[1,0]
	v_pk_mul_f32 v[34:35], v[34:35], v[2:3] op_sel_hi:[1,0]
	v_pk_mul_f32 v[32:33], v[32:33], v[2:3] op_sel_hi:[1,0]
	v_pk_mul_f32 v[30:31], v[30:31], v[2:3] op_sel_hi:[1,0]
	v_pk_mul_f32 v[28:29], v[28:29], v[2:3] op_sel_hi:[1,0]
	v_pk_mul_f32 v[26:27], v[26:27], v[2:3] op_sel_hi:[1,0]
	v_pk_mul_f32 v[24:25], v[24:25], v[2:3] op_sel_hi:[1,0]
	v_pk_mul_f32 v[22:23], v[22:23], v[2:3] op_sel_hi:[1,0]
	v_pk_mul_f32 v[20:21], v[20:21], v[2:3] op_sel_hi:[1,0]
	v_pk_mul_f32 v[18:19], v[18:19], v[2:3] op_sel_hi:[1,0]
	v_pk_mul_f32 v[16:17], v[16:17], v[2:3] op_sel_hi:[1,0]
	v_pk_add_f32 v[100:101], v[100:101], v[0:1] op_sel_hi:[1,0] neg_lo:[0,1] neg_hi:[0,1]
	v_pk_add_f32 v[102:103], v[102:103], v[0:1] op_sel_hi:[1,0] neg_lo:[0,1] neg_hi:[0,1]
	v_pk_add_f32 v[104:105], v[104:105], v[0:1] op_sel_hi:[1,0] neg_lo:[0,1] neg_hi:[0,1]
	v_pk_add_f32 v[106:107], v[106:107], v[0:1] op_sel_hi:[1,0] neg_lo:[0,1] neg_hi:[0,1]
	v_pk_add_f32 v[108:109], v[108:109], v[0:1] op_sel_hi:[1,0] neg_lo:[0,1] neg_hi:[0,1]
	v_pk_add_f32 v[110:111], v[110:111], v[0:1] op_sel_hi:[1,0] neg_lo:[0,1] neg_hi:[0,1]
	v_pk_add_f32 v[80:81], v[80:81], v[0:1] op_sel_hi:[1,0] neg_lo:[0,1] neg_hi:[0,1]
	v_pk_add_f32 v[82:83], v[82:83], v[0:1] op_sel_hi:[1,0] neg_lo:[0,1] neg_hi:[0,1]
	v_pk_add_f32 v[84:85], v[84:85], v[0:1] op_sel_hi:[1,0] neg_lo:[0,1] neg_hi:[0,1]
	v_pk_add_f32 v[86:87], v[86:87], v[0:1] op_sel_hi:[1,0] neg_lo:[0,1] neg_hi:[0,1]
	v_pk_add_f32 v[88:89], v[88:89], v[0:1] op_sel_hi:[1,0] neg_lo:[0,1] neg_hi:[0,1]
	v_pk_add_f32 v[90:91], v[90:91], v[0:1] op_sel_hi:[1,0] neg_lo:[0,1] neg_hi:[0,1]
	v_pk_add_f32 v[92:93], v[92:93], v[0:1] op_sel_hi:[1,0] neg_lo:[0,1] neg_hi:[0,1]
	v_pk_add_f32 v[94:95], v[94:95], v[0:1] op_sel_hi:[1,0] neg_lo:[0,1] neg_hi:[0,1]
	v_mul_f32_e32 v151, v151, v2

; #define MFMA32(a, b, c) __builtin_amdgcn_mfma_f32_32x32x16_bf16((a), (b), (c), 0, 0, 0)
; template <int DQK, int KROW, bool BIAS, bool MAPS2>
; DI void attn_core(const int t, const u16* __restrict__ Q, int ldq, const u16* __restrict__ Kp, int ldk, const u16* __restrict__ Vt, int q0,
;                   char* lds, const float* lut, float b31, f32x16 (&o)[4], float& l_out) {
;     ...
;       const bool far = BIAS && (wq0 - (k0 + 63) >= 128);
;       const float init = (far ? b31 : 0.f) - m_run;
; #pragma unroll
;       for (int k2 = 0; k2 < 2; ++k2)
; #pragma unroll
;         for (int i = 0; i < 16; ++i) s[k2][i] = init;
;       {
;         constexpr int QBS = (NKS > 4) ? 2 : 4, NBT = NKS / QBS;
;         bf16x8 kfb[2][QBS][2];
;         const char* kbase = lds + (kt & 1) * AT_KBUF + r * KS + hf * 16 + map * (DQK * 2);
; #pragma unroll
;         for (int jq = 0; jq < QBS; ++jq)
; #pragma unroll
;           for (int k2 = 0; k2 < 2; ++k2) kfb[0][jq][k2] = *(const bf16x8*)(kbase + 32 * k2 * KS + jq * 32);
; #pragma unroll
;         for (int b = 0; b < NBT; ++b) {
;           if (b + 1 < NBT) {
; #pragma unroll
;             for (int jq = 0; jq < QBS; ++jq)
; #pragma unroll
;               for (int k2 = 0; k2 < 2; ++k2) kfb[(b + 1) & 1][jq][k2] = *(const bf16x8*)(kbase + 32 * k2 * KS + ((b + 1) * QBS + jq) * 32);
;           }
;           __builtin_amdgcn_sched_barrier(0);
;           __builtin_amdgcn_s_setprio(1);
; #pragma unroll
;           for (int jq = 0; jq < QBS; ++jq)
; #pragma unroll
;             for (int k2 = 0; k2 < 2; ++k2) s[k2] = MFMA32(kfb[b & 1][jq][k2], qf[b * QBS + jq], s[k2]);
;           __builtin_amdgcn_s_setprio(0);
;           __builtin_amdgcn_sched_barrier(0);
;         }
;       }
;       if (BIAS && !far) {
; #pragma unroll
;         for (int k2 = 0; k2 < 2; ++k2)
; #pragma unroll
;           for (int i = 0; i < 16; ++i) {
;             const int key = k0 + 32 * k2 + (i & 3) + 8 * (i >> 2) + 4 * hf;
;             int d = qrow - key; d = d < 0 ? 0 : (d > 128 ? 128 : d);
;             s[k2][i] += lut[d];
;           }
;       }
;       if (k0 + 63 > wq0) {
; #pragma unroll
;         for (int k2 = 0; k2 < 2; ++k2)
; #pragma unroll
;           for (int i = 0; i < 16; ++i) {
;             const int key = k0 + 32 * k2 + (i & 3) + 8 * (i >> 2) + 4 * hf;
;             if (key > qrow) s[k2][i] = -INFINITY;
;           }
;       }
.LBB0_256:
	s_add_i32 s0, s4, 0xffffff80
	v_cmp_le_i32_e32 vcc, s0, v177
	s_and_saveexec_b64 s[90:91], vcc
	s_cbranch_execz .LBB0_262
	s_cmp_eq_u32 s93, 0
	s_cselect_b32 s97, 0xff800000, s6
	s_and_b32 s92, s93, 1
	s_mul_i32 s0, s92, 0x6400
	v_add_u32_e32 v181, s0, v178
	ds_read_b128 v[182:185], v181
	ds_read_b128 v[186:189], v181 offset:32
	ds_read_b128 v[190:193], v181 offset:12800
	ds_read_b128 v[194:197], v181 offset:12832
	ds_read_b128 v[198:201], v181 offset:64
	ds_read_b128 v[202:205], v181 offset:96
	ds_read_b128 v[206:209], v181 offset:12864
	ds_read_b128 v[210:213], v181 offset:12896
	v_sub_f32_e32 v66, 0, v180
	s_setprio 1
	v_mov_b32_e32 v67, v66
	v_mov_b32_e32 v68, v66
	v_mov_b32_e32 v69, v66
	v_mov_b32_e32 v70, v66
	v_mov_b32_e32 v71, v66
	v_mov_b32_e32 v72, v66
	v_mov_b32_e32 v73, v66
	v_mov_b32_e32 v74, v66
	v_mov_b32_e32 v75, v66
	v_mov_b32_e32 v76, v66
	v_mov_b32_e32 v77, v66
	v_mov_b32_e32 v78, v66
	v_mov_b32_e32 v79, v66
	v_mov_b32_e32 v80, v66
	v_mov_b32_e32 v81, v66
	s_waitcnt vmcnt(16) lgkmcnt(7)
	s_nop 0
	v_mfma_f32_32x32x16_bf16 v[82:97], v[182:185], v[98:101], v[66:81]
	s_waitcnt lgkmcnt(5)
	v_mfma_f32_32x32x16_bf16 v[66:81], v[190:193], v[98:101], v[66:81]
	s_waitcnt vmcnt(15)
	v_mfma_f32_32x32x16_bf16 v[82:97], v[186:189], v[102:105], v[82:97]
	s_waitcnt lgkmcnt(4)
	v_mfma_f32_32x32x16_bf16 v[66:81], v[194:197], v[102:105], v[66:81]
	s_setprio 0
	ds_read_b128 v[182:185], v181 offset:128
	ds_read_b128 v[186:189], v181 offset:160
	ds_read_b128 v[190:193], v181 offset:12928
	ds_read_b128 v[194:197], v181 offset:12960
	s_setprio 1
	s_waitcnt vmcnt(14) lgkmcnt(7)
	v_mfma_f32_32x32x16_bf16 v[82:97], v[198:201], v[106:109], v[82:97]
	s_waitcnt lgkmcnt(5)
	v_mfma_f32_32x32x16_bf16 v[66:81], v[206:209], v[106:109], v[66:81]
	s_waitcnt vmcnt(13)
	v_mfma_f32_32x32x16_bf16 v[82:97], v[202:205], v[110:113], v[82:97]
	s_waitcnt lgkmcnt(4)
	v_mfma_f32_32x32x16_bf16 v[66:81], v[210:213], v[110:113], v[66:81]
	s_setprio 0
	ds_read_b128 v[198:201], v181 offset:192
	ds_read_b128 v[202:205], v181 offset:224
	ds_read_b128 v[206:209], v181 offset:12992
	ds_read_b128 v[210:213], v181 offset:13024
	s_setprio 1
	s_waitcnt vmcnt(12) lgkmcnt(7)
	v_mfma_f32_32x32x16_bf16 v[82:97], v[182:185], v[114:117], v[82:97]
	s_waitcnt lgkmcnt(5)
	v_mfma_f32_32x32x16_bf16 v[66:81], v[190:193], v[114:117], v[66:81]
	s_waitcnt vmcnt(11)
	v_mfma_f32_32x32x16_bf16 v[82:97], v[186:189], v[118:121], v[82:97]
	s_waitcnt lgkmcnt(4)
	v_mfma_f32_32x32x16_bf16 v[66:81], v[194:197], v[118:121], v[66:81]
	s_setprio 0
	ds_read_b128 v[182:185], v181 offset:256
	ds_read_b128 v[186:189], v181 offset:288
	ds_read_b128 v[190:193], v181 offset:13056
	ds_read_b128 v[194:197], v181 offset:13088
	s_setprio 1
	s_waitcnt vmcnt(10) lgkmcnt(7)
	v_mfma_f32_32x32x16_bf16 v[82:97], v[198:201], v[122:125], v[82:97]
	s_waitcnt lgkmcnt(5)
	v_mfma_f32_32x32x16_bf16 v[66:81], v[206:209], v[122:125], v[66:81]
	s_waitcnt vmcnt(9)
	v_mfma_f32_32x32x16_bf16 v[82:97], v[202:205], v[126:129], v[82:97]
	s_waitcnt lgkmcnt(4)
	v_mfma_f32_32x32x16_bf16 v[66:81], v[210:213], v[126:129], v[66:81]
	s_setprio 0
	ds_read_b128 v[198:201], v181 offset:320
	ds_read_b128 v[202:205], v181 offset:352
	ds_read_b128 v[206:209], v181 offset:13120
	ds_read_b128 v[210:213], v181 offset:13152
	s_setprio 1
	s_waitcnt vmcnt(8) lgkmcnt(7)
	v_mfma_f32_32x32x16_bf16 v[82:97], v[182:185], v[130:133], v[82:97]
	s_waitcnt lgkmcnt(5)
	v_mfma_f32_32x32x16_bf16 v[66:81], v[190:193], v[130:133], v[66:81]
	s_waitcnt vmcnt(7)
	v_mfma_f32_32x32x16_bf16 v[82:97], v[186:189], v[134:137], v[82:97]
	s_waitcnt lgkmcnt(4)
	v_mfma_f32_32x32x16_bf16 v[66:81], v[194:197], v[134:137], v[66:81]
	s_setprio 0
	s_setprio 1
	s_waitcnt vmcnt(6) lgkmcnt(3)
	v_mfma_f32_32x32x16_bf16 v[82:97], v[198:201], v[138:141], v[82:97]
	s_waitcnt lgkmcnt(1)
	v_mfma_f32_32x32x16_bf16 v[66:81], v[206:209], v[138:141], v[66:81]
	s_waitcnt vmcnt(5)
	v_mfma_f32_32x32x16_bf16 v[82:97], v[202:205], v[142:145], v[82:97]
	s_waitcnt lgkmcnt(0)
	v_mfma_f32_32x32x16_bf16 v[66:81], v[210:213], v[142:145], v[66:81]
	s_setprio 0
	s_add_i32 s0, s4, 0xffffffbf
	v_cmp_gt_i32_e32 vcc, s0, v167
	s_and_saveexec_b64 s[0:1], vcc
	s_cbranch_execz .LBB0_259
	v_add_u32_e32 v181, s4, v176
	v_add_u32_e32 v182, 0xffffff80, v181
	v_cmp_gt_i32_e32 vcc, v182, v170
	s_nop 1
	v_cndmask_b32_e32 v183, v82, v230, vcc
	v_cmp_lt_i32_e32 vcc, v182, v170
	v_add_u32_e32 v182, 0xffffff82, v181
	s_nop 0
	v_cndmask_b32_e32 v82, v183, v82, vcc
	v_cndmask_b32_e32 v83, v230, v83, vcc
	v_cmp_le_i32_e32 vcc, v182, v170
	v_add_u32_e32 v182, 0xffffff83, v181
	s_nop 0
	v_cndmask_b32_e32 v84, v230, v84, vcc
	v_cmp_le_i32_e32 vcc, v182, v170
	v_add_u32_e32 v182, 0xffffff88, v181
	s_nop 0
	v_cndmask_b32_e32 v85, v230, v85, vcc
	v_cmp_le_i32_e32 vcc, v182, v170
	v_add_u32_e32 v182, 0xffffff89, v181
	s_nop 0
	v_cndmask_b32_e32 v86, v230, v86, vcc
	v_cmp_le_i32_e32 vcc, v182, v170
	v_add_u32_e32 v182, 0xffffff8a, v181
	s_nop 0
	v_cndmask_b32_e32 v87, v230, v87, vcc
	v_cmp_le_i32_e32 vcc, v182, v170
	v_add_u32_e32 v182, 0xffffff8b, v181
	s_nop 0
	v_cndmask_b32_e32 v88, v230, v88, vcc
	v_cmp_le_i32_e32 vcc, v182, v170
	v_add_u32_e32 v182, 0xffffff90, v181
	s_nop 0
	v_cndmask_b32_e32 v89, v230, v89, vcc
	v_cmp_le_i32_e32 vcc, v182, v170
	v_add_u32_e32 v182, 0xffffff91, v181
	s_nop 0
	v_cndmask_b32_e32 v90, v230, v90, vcc
	v_cmp_le_i32_e32 vcc, v182, v170
	v_add_u32_e32 v182, 0xffffff92, v181
	s_nop 0
	v_cndmask_b32_e32 v91, v230, v91, vcc
	v_cmp_le_i32_e32 vcc, v182, v170
	v_add_u32_e32 v182, 0xffffff93, v181
	s_nop 0
	v_cndmask_b32_e32 v92, v230, v92, vcc
	v_cmp_le_i32_e32 vcc, v182, v170
	v_add_u32_e32 v182, 0xffffff98, v181
; template <int DQK, int KROW, bool BIAS, bool MAPS2>
; DI void attn_core(const int t, const u16* __restrict__ Q, int ldq, const u16* __restrict__ Kp, int ldk, const u16* __restrict__ Vt, int q0,
;                   char* lds, const float* lut, float b31, f32x16 (&o)[4], float& l_out) {
;     ...
;       if (k0 + 63 > wq0) {
; #pragma unroll
;         for (int k2 = 0; k2 < 2; ++k2)
; #pragma unroll
;           for (int i = 0; i < 16; ++i) {
;             const int key = k0 + 32 * k2 + (i & 3) + 8 * (i >> 2) + 4 * hf;
;             if (key > qrow) s[k2][i] = -INFINITY;
;           }
;       }
;       float mx = s[0][0];
; #pragma unroll
;       for (int k2 = 0; k2 < 2; ++k2)
; #pragma unroll
;         for (int i = 0; i < 16; ++i) mx = fmaxf(mx, s[k2][i]);
;       mx = xhalf_max(mx);
;       if (__builtin_amdgcn_ballot_w64(kt == 0 || mx > RESCALE_THR)) {
;         const float delta = (kt == 0) ? mx : fmaxf(mx, 0.f);
;         const float alpha = __builtin_amdgcn_exp2f(-delta);
;         m_run += delta;
;         l_run *= alpha;
; #pragma unroll
;         for (int dt = 0; dt < 4; ++dt)
; #pragma unroll
;           for (int i = 0; i < 16; ++i) o[dt][i] *= alpha;
; #pragma unroll
;         for (int k2 = 0; k2 < 2; ++k2)
; #pragma unroll
;           for (int i = 0; i < 16; ++i) s[k2][i] -= delta;
;       }
	s_nop 0
	v_cndmask_b32_e32 v93, v230, v93, vcc
	v_cmp_le_i32_e32 vcc, v182, v170
	v_add_u32_e32 v182, 0xffffff99, v181
	s_nop 0
	v_cndmask_b32_e32 v94, v230, v94, vcc
	v_cmp_le_i32_e32 vcc, v182, v170
	v_add_u32_e32 v182, 0xffffff9a, v181
	s_nop 0
	v_cndmask_b32_e32 v95, v230, v95, vcc
	v_cmp_le_i32_e32 vcc, v182, v170
	v_add_u32_e32 v182, 0xffffff9b, v181
	s_nop 0
	v_cndmask_b32_e32 v96, v230, v96, vcc
	v_cmp_le_i32_e32 vcc, v182, v170
	v_add_u32_e32 v182, 0xffffffa0, v181
	s_nop 0
	v_cndmask_b32_e32 v97, v230, v97, vcc
	v_cmp_le_i32_e32 vcc, v182, v170
	v_add_u32_e32 v182, 0xffffffa1, v181
	s_nop 0
	v_cndmask_b32_e32 v66, v230, v66, vcc
	v_cmp_le_i32_e32 vcc, v182, v170
	v_add_u32_e32 v182, 0xffffffa2, v181
	s_nop 0
	v_cndmask_b32_e32 v67, v230, v67, vcc
	v_cmp_le_i32_e32 vcc, v182, v170
	v_add_u32_e32 v182, 0xffffffa3, v181
	s_nop 0
	v_cndmask_b32_e32 v68, v230, v68, vcc
	v_cmp_le_i32_e32 vcc, v182, v170
	v_add_u32_e32 v182, 0xffffffa8, v181
	s_nop 0
	v_cndmask_b32_e32 v69, v230, v69, vcc
	v_cmp_le_i32_e32 vcc, v182, v170
	v_add_u32_e32 v182, 0xffffffa9, v181
	s_nop 0
	v_cndmask_b32_e32 v70, v230, v70, vcc
	v_cmp_le_i32_e32 vcc, v182, v170
	v_add_u32_e32 v182, 0xffffffaa, v181
	s_nop 0
	v_cndmask_b32_e32 v71, v230, v71, vcc
	v_cmp_le_i32_e32 vcc, v182, v170
	v_add_u32_e32 v182, 0xffffffab, v181
	s_nop 0
	v_cndmask_b32_e32 v72, v230, v72, vcc
	v_cmp_le_i32_e32 vcc, v182, v170
	v_add_u32_e32 v182, 0xffffffb0, v181
	s_nop 0
	v_cndmask_b32_e32 v73, v230, v73, vcc
	v_cmp_le_i32_e32 vcc, v182, v170
	v_add_u32_e32 v182, 0xffffffb1, v181
	s_nop 0
	v_cndmask_b32_e32 v74, v230, v74, vcc
	v_cmp_le_i32_e32 vcc, v182, v170
	v_add_u32_e32 v182, 0xffffffb2, v181
	s_nop 0
	v_cndmask_b32_e32 v75, v230, v75, vcc
	v_cmp_le_i32_e32 vcc, v182, v170
	v_add_u32_e32 v182, 0xffffffb3, v181
	s_nop 0
	v_cndmask_b32_e32 v76, v230, v76, vcc
	v_cmp_le_i32_e32 vcc, v182, v170
	v_add_u32_e32 v182, 0xffffffb8, v181
	s_nop 0
	v_cndmask_b32_e32 v77, v230, v77, vcc
	v_cmp_le_i32_e32 vcc, v182, v170
	v_add_u32_e32 v182, 0xffffffb9, v181
	s_nop 0
	v_cndmask_b32_e32 v78, v230, v78, vcc
	v_cmp_le_i32_e32 vcc, v182, v170
	v_add_u32_e32 v182, 0xffffffba, v181
	v_add_u32_e32 v181, 0xffffffbb, v181
	v_cndmask_b32_e32 v79, v230, v79, vcc
	v_cmp_le_i32_e32 vcc, v182, v170
	s_nop 1
	v_cndmask_b32_e32 v80, v230, v80, vcc
	v_cmp_le_i32_e32 vcc, v181, v170
	s_nop 1
	v_cndmask_b32_e32 v81, v230, v81, vcc
.LBB0_259:
	s_or_b64 exec, exec, s[0:1]
	s_nop 3
	v_max_f32_e32 v181, v83, v83
	v_max_f32_e32 v182, v82, v82
	v_max_f32_e32 v181, v182, v181
	v_max3_f32 v181, v181, v84, v85
	v_max3_f32 v181, v181, v86, v87
	v_max3_f32 v181, v181, v88, v89
	v_max3_f32 v181, v181, v90, v91
	v_max3_f32 v181, v181, v92, v93
	v_max3_f32 v181, v181, v94, v95
	v_max3_f32 v181, v181, v96, v97
	v_max3_f32 v181, v181, v66, v67
	v_max3_f32 v181, v181, v68, v69
	v_max3_f32 v181, v181, v70, v71
	v_max3_f32 v181, v181, v72, v73
	v_max3_f32 v181, v181, v74, v75
	v_max3_f32 v181, v181, v76, v77
	v_max3_f32 v181, v181, v78, v79
	v_max3_f32 v181, v181, v80, v81
	v_mov_b32_e32 v182, v181
	s_nop 1
	v_permlane32_swap_b32_e32 v181, v182
	v_max_f32_e32 v181, v181, v182
	v_cmp_lt_f32_e32 vcc, s97, v181
	s_cbranch_vccz .LBB0_261
	s_cmp_eq_u32 s93, 0
	s_cselect_b64 s[0:1], -1, 0
	v_max_f32_e32 v182, v181, v181
	v_max_f32_e32 v182, 0, v182
	v_cndmask_b32_e64 v182, v182, v181, s[0:1]
	v_exp_f32_e64 v184, -v182
	v_add_f32_e32 v180, v180, v182
	v_pk_add_f32 v[82:83], v[82:83], v[182:183] op_sel_hi:[1,0] neg_lo:[0,1] neg_hi:[0,1]
	v_pk_add_f32 v[84:85], v[84:85], v[182:183] op_sel_hi:[1,0] neg_lo:[0,1] neg_hi:[0,1]
	v_pk_mul_f32 v[64:65], v[64:65], v[184:185] op_sel_hi:[1,0]
	v_pk_mul_f32 v[62:63], v[62:63], v[184:185] op_sel_hi:[1,0]
	v_pk_mul_f32 v[60:61], v[60:61], v[184:185] op_sel_hi:[1,0]
	v_pk_mul_f32 v[58:59], v[58:59], v[184:185] op_sel_hi:[1,0]
	v_pk_mul_f32 v[56:57], v[56:57], v[184:185] op_sel_hi:[1,0]
	v_pk_mul_f32 v[54:55], v[54:55], v[184:185] op_sel_hi:[1,0]
	v_pk_mul_f32 v[52:53], v[52:53], v[184:185] op_sel_hi:[1,0]
	v_pk_mul_f32 v[50:51], v[50:51], v[184:185] op_sel_hi:[1,0]
	v_pk_mul_f32 v[48:49], v[48:49], v[184:185] op_sel_hi:[1,0]
	v_pk_mul_f32 v[46:47], v[46:47], v[184:185] op_sel_hi:[1,0]
	v_pk_mul_f32 v[44:45], v[44:45], v[184:185] op_sel_hi:[1,0]
	v_pk_mul_f32 v[42:43], v[42:43], v[184:185] op_sel_hi:[1,0]
	v_pk_mul_f32 v[40:41], v[40:41], v[184:185] op_sel_hi:[1,0]
	v_pk_mul_f32 v[38:39], v[38:39], v[184:185] op_sel_hi:[1,0]
	v_pk_mul_f32 v[36:37], v[36:37], v[184:185] op_sel_hi:[1,0]
	v_pk_mul_f32 v[34:35], v[34:35], v[184:185] op_sel_hi:[1,0]
	v_pk_mul_f32 v[32:33], v[32:33], v[184:185] op_sel_hi:[1,0]
	v_pk_mul_f32 v[30:31], v[30:31], v[184:185] op_sel_hi:[1,0]
	v_pk_mul_f32 v[28:29], v[28:29], v[184:185] op_sel_hi:[1,0]
	v_pk_mul_f32 v[26:27], v[26:27], v[184:185] op_sel_hi:[1,0]
	v_pk_mul_f32 v[24:25], v[24:25], v[184:185] op_sel_hi:[1,0]
	v_pk_mul_f32 v[22:23], v[22:23], v[184:185] op_sel_hi:[1,0]
	v_pk_mul_f32 v[20:21], v[20:21], v[184:185] op_sel_hi:[1,0]
	v_pk_mul_f32 v[18:19], v[18:19], v[184:185] op_sel_hi:[1,0]
	v_pk_mul_f32 v[16:17], v[16:17], v[184:185] op_sel_hi:[1,0]
	v_pk_mul_f32 v[14:15], v[14:15], v[184:185] op_sel_hi:[1,0]
	v_pk_mul_f32 v[12:13], v[12:13], v[184:185] op_sel_hi:[1,0]
	v_pk_mul_f32 v[10:11], v[10:11], v[184:185] op_sel_hi:[1,0]
	v_pk_mul_f32 v[8:9], v[8:9], v[184:185] op_sel_hi:[1,0]
	v_pk_mul_f32 v[6:7], v[6:7], v[184:185] op_sel_hi:[1,0]
	v_pk_mul_f32 v[4:5], v[4:5], v[184:185] op_sel_hi:[1,0]
	v_pk_mul_f32 v[2:3], v[2:3], v[184:185] op_sel_hi:[1,0]
	v_pk_add_f32 v[86:87], v[86:87], v[182:183] op_sel_hi:[1,0] neg_lo:[0,1] neg_hi:[0,1]
	v_pk_add_f32 v[88:89], v[88:89], v[182:183] op_sel_hi:[1,0] neg_lo:[0,1] neg_hi:[0,1]
	v_pk_add_f32 v[90:91], v[90:91], v[182:183] op_sel_hi:[1,0] neg_lo:[0,1] neg_hi:[0,1]
	v_pk_add_f32 v[92:93], v[92:93], v[182:183] op_sel_hi:[1,0] neg_lo:[0,1] neg_hi:[0,1]
	v_pk_add_f32 v[94:95], v[94:95], v[182:183] op_sel_hi:[1,0] neg_lo:[0,1] neg_hi:[0,1]
	v_pk_add_f32 v[96:97], v[96:97], v[182:183] op_sel_hi:[1,0] neg_lo:[0,1] neg_hi:[0,1]
	v_pk_add_f32 v[66:67], v[66:67], v[182:183] op_sel_hi:[1,0] neg_lo:[0,1] neg_hi:[0,1]
	v_pk_add_f32 v[68:69], v[68:69], v[182:183] op_sel_hi:[1,0] neg_lo:[0,1] neg_hi:[0,1]
	v_pk_add_f32 v[70:71], v[70:71], v[182:183] op_sel_hi:[1,0] neg_lo:[0,1] neg_hi:[0,1]
	v_pk_add_f32 v[72:73], v[72:73], v[182:183] op_sel_hi:[1,0] neg_lo:[0,1] neg_hi:[0,1]
	v_pk_add_f32 v[74:75], v[74:75], v[182:183] op_sel_hi:[1,0] neg_lo:[0,1] neg_hi:[0,1]
	v_pk_add_f32 v[76:77], v[76:77], v[182:183] op_sel_hi:[1,0] neg_lo:[0,1] neg_hi:[0,1]
	v_pk_add_f32 v[78:79], v[78:79], v[182:183] op_sel_hi:[1,0] neg_lo:[0,1] neg_hi:[0,1]
	v_pk_add_f32 v[80:81], v[80:81], v[182:183] op_sel_hi:[1,0] neg_lo:[0,1] neg_hi:[0,1]
	v_mul_f32_e32 v0, v0, v184

; #define MFMA32(a, b, c) __builtin_amdgcn_mfma_f32_32x32x16_bf16((a), (b), (c), 0, 0, 0)
; template <int DQK, int KROW, bool BIAS, bool MAPS2>
; DI void attn_core(const int t, const u16* __restrict__ Q, int ldq, const u16* __restrict__ Kp, int ldk, const u16* __restrict__ Vt, int q0,
;                   char* lds, const float* lut, float b31, f32x16 (&o)[4], float& l_out) {
;     ...
;       const bool far = BIAS && (wq0 - (k0 + 63) >= 128);
;       const float init = (far ? b31 : 0.f) - m_run;
; #pragma unroll
;       for (int k2 = 0; k2 < 2; ++k2)
; #pragma unroll
;         for (int i = 0; i < 16; ++i) s[k2][i] = init;
;       {
;         constexpr int QBS = (NKS > 4) ? 2 : 4, NBT = NKS / QBS;
;         bf16x8 kfb[2][QBS][2];
;         const char* kbase = lds + (kt & 1) * AT_KBUF + r * KS + hf * 16 + map * (DQK * 2);
; #pragma unroll
;         for (int jq = 0; jq < QBS; ++jq)
; #pragma unroll
;           for (int k2 = 0; k2 < 2; ++k2) kfb[0][jq][k2] = *(const bf16x8*)(kbase + 32 * k2 * KS + jq * 32);
; #pragma unroll
;         for (int b = 0; b < NBT; ++b) {
;           if (b + 1 < NBT) {
; #pragma unroll
;             for (int jq = 0; jq < QBS; ++jq)
; #pragma unroll
;               for (int k2 = 0; k2 < 2; ++k2) kfb[(b + 1) & 1][jq][k2] = *(const bf16x8*)(kbase + 32 * k2 * KS + ((b + 1) * QBS + jq) * 32);
;           }
;           __builtin_amdgcn_sched_barrier(0);
;           __builtin_amdgcn_s_setprio(1);
; #pragma unroll
;           for (int jq = 0; jq < QBS; ++jq)
; #pragma unroll
;             for (int k2 = 0; k2 < 2; ++k2) s[k2] = MFMA32(kfb[b & 1][jq][k2], qf[b * QBS + jq], s[k2]);
;           __builtin_amdgcn_s_setprio(0);
;           __builtin_amdgcn_sched_barrier(0);
;         }
;       }
;       if (BIAS && !far) {
; #pragma unroll
;         for (int k2 = 0; k2 < 2; ++k2)
; #pragma unroll
;           for (int i = 0; i < 16; ++i) {
;             const int key = k0 + 32 * k2 + (i & 3) + 8 * (i >> 2) + 4 * hf;
;             int d = qrow - key; d = d < 0 ? 0 : (d > 128 ? 128 : d);
;             s[k2][i] += lut[d];
;           }
;       }
;       if (k0 + 63 > wq0) {
; #pragma unroll
;         for (int k2 = 0; k2 < 2; ++k2)
; #pragma unroll
;           for (int i = 0; i < 16; ++i) {
;             const int key = k0 + 32 * k2 + (i & 3) + 8 * (i >> 2) + 4 * hf;
;             if (key > qrow) s[k2][i] = -INFINITY;
;           }
;       }
.LBB0_270:
	s_add_i32 s0, s4, 0xffffff80
	v_cmp_le_i32_e32 vcc, s0, v177
	s_and_saveexec_b64 s[90:91], vcc
	s_cbranch_execz .LBB0_276
	s_cmp_eq_u32 s63, 0
	s_cselect_b32 s97, 0xff800000, s6
	s_and_b32 s62, s63, 1
	s_mul_i32 s0, s62, 0x6400
	v_add_u32_e32 v181, s0, v178
	ds_read_b128 v[182:185], v181
	ds_read_b128 v[186:189], v181 offset:32
	ds_read_b128 v[190:193], v181 offset:12800
	ds_read_b128 v[194:197], v181 offset:12832
	ds_read_b128 v[198:201], v181 offset:64
	ds_read_b128 v[202:205], v181 offset:96
	ds_read_b128 v[206:209], v181 offset:12864
	ds_read_b128 v[210:213], v181 offset:12896
	v_sub_f32_e32 v66, 0, v180
	s_setprio 1
	v_mov_b32_e32 v67, v66
	v_mov_b32_e32 v68, v66
	v_mov_b32_e32 v69, v66
	v_mov_b32_e32 v70, v66
	v_mov_b32_e32 v71, v66
	v_mov_b32_e32 v72, v66
	v_mov_b32_e32 v73, v66
	v_mov_b32_e32 v74, v66
	v_mov_b32_e32 v75, v66
	v_mov_b32_e32 v76, v66
	v_mov_b32_e32 v77, v66
	v_mov_b32_e32 v78, v66
	v_mov_b32_e32 v79, v66
	v_mov_b32_e32 v80, v66
	v_mov_b32_e32 v81, v66
	s_waitcnt vmcnt(16) lgkmcnt(7)
	s_nop 0
	v_mfma_f32_32x32x16_bf16 v[82:97], v[182:185], v[98:101], v[66:81]
	s_waitcnt lgkmcnt(5)
	v_mfma_f32_32x32x16_bf16 v[66:81], v[190:193], v[98:101], v[66:81]
	s_waitcnt vmcnt(15)
	v_mfma_f32_32x32x16_bf16 v[82:97], v[186:189], v[102:105], v[82:97]
	s_waitcnt lgkmcnt(4)
	v_mfma_f32_32x32x16_bf16 v[66:81], v[194:197], v[102:105], v[66:81]
	s_setprio 0
	ds_read_b128 v[182:185], v181 offset:128
	ds_read_b128 v[186:189], v181 offset:160
	ds_read_b128 v[190:193], v181 offset:12928
	ds_read_b128 v[194:197], v181 offset:12960
	s_setprio 1
	s_waitcnt vmcnt(14) lgkmcnt(7)
	v_mfma_f32_32x32x16_bf16 v[82:97], v[198:201], v[106:109], v[82:97]
	s_waitcnt lgkmcnt(5)
	v_mfma_f32_32x32x16_bf16 v[66:81], v[206:209], v[106:109], v[66:81]
	s_waitcnt vmcnt(13)
	v_mfma_f32_32x32x16_bf16 v[82:97], v[202:205], v[110:113], v[82:97]
	s_waitcnt lgkmcnt(4)
	v_mfma_f32_32x32x16_bf16 v[66:81], v[210:213], v[110:113], v[66:81]
	s_setprio 0
	ds_read_b128 v[198:201], v181 offset:192
	ds_read_b128 v[202:205], v181 offset:224
	ds_read_b128 v[206:209], v181 offset:12992
	ds_read_b128 v[210:213], v181 offset:13024
	s_setprio 1
	s_waitcnt vmcnt(12) lgkmcnt(7)
	v_mfma_f32_32x32x16_bf16 v[82:97], v[182:185], v[114:117], v[82:97]
	s_waitcnt lgkmcnt(5)
	v_mfma_f32_32x32x16_bf16 v[66:81], v[190:193], v[114:117], v[66:81]
	s_waitcnt vmcnt(11)
	v_mfma_f32_32x32x16_bf16 v[82:97], v[186:189], v[118:121], v[82:97]
	s_waitcnt lgkmcnt(4)
	v_mfma_f32_32x32x16_bf16 v[66:81], v[194:197], v[118:121], v[66:81]
	s_setprio 0
	ds_read_b128 v[182:185], v181 offset:256
	ds_read_b128 v[186:189], v181 offset:288
	ds_read_b128 v[190:193], v181 offset:13056
	ds_read_b128 v[194:197], v181 offset:13088
	s_setprio 1
	s_waitcnt vmcnt(10) lgkmcnt(7)
	v_mfma_f32_32x32x16_bf16 v[82:97], v[198:201], v[122:125], v[82:97]
	s_waitcnt lgkmcnt(5)
	v_mfma_f32_32x32x16_bf16 v[66:81], v[206:209], v[122:125], v[66:81]
	s_waitcnt vmcnt(9)
	v_mfma_f32_32x32x16_bf16 v[82:97], v[202:205], v[126:129], v[82:97]
	s_waitcnt lgkmcnt(4)
	v_mfma_f32_32x32x16_bf16 v[66:81], v[210:213], v[126:129], v[66:81]
	s_setprio 0
	ds_read_b128 v[198:201], v181 offset:320
	ds_read_b128 v[202:205], v181 offset:352
	ds_read_b128 v[206:209], v181 offset:13120
	ds_read_b128 v[210:213], v181 offset:13152
	s_setprio 1
	s_waitcnt vmcnt(8) lgkmcnt(7)
	v_mfma_f32_32x32x16_bf16 v[82:97], v[182:185], v[130:133], v[82:97]
	s_waitcnt lgkmcnt(5)
	v_mfma_f32_32x32x16_bf16 v[66:81], v[190:193], v[130:133], v[66:81]
	s_waitcnt vmcnt(7)
	v_mfma_f32_32x32x16_bf16 v[82:97], v[186:189], v[134:137], v[82:97]
	s_waitcnt lgkmcnt(4)
	v_mfma_f32_32x32x16_bf16 v[66:81], v[194:197], v[134:137], v[66:81]
	s_setprio 0
	s_setprio 1
	s_waitcnt vmcnt(6) lgkmcnt(3)
	v_mfma_f32_32x32x16_bf16 v[82:97], v[198:201], v[138:141], v[82:97]
	s_waitcnt lgkmcnt(1)
	v_mfma_f32_32x32x16_bf16 v[66:81], v[206:209], v[138:141], v[66:81]
	s_waitcnt vmcnt(5)
	v_mfma_f32_32x32x16_bf16 v[82:97], v[202:205], v[142:145], v[82:97]
	s_waitcnt lgkmcnt(0)
	v_mfma_f32_32x32x16_bf16 v[66:81], v[210:213], v[142:145], v[66:81]
	s_setprio 0
	s_add_i32 s0, s4, 0xffffffbf
	v_cmp_gt_i32_e32 vcc, s0, v167
	s_and_saveexec_b64 s[0:1], vcc
	s_cbranch_execz .LBB0_273
	v_add_u32_e32 v181, s4, v176
	v_add_u32_e32 v182, 0xffffff80, v181
	v_cmp_gt_i32_e32 vcc, v182, v170
	s_nop 1
	v_cndmask_b32_e32 v183, v82, v230, vcc
	v_cmp_lt_i32_e32 vcc, v182, v170
	v_add_u32_e32 v182, 0xffffff82, v181
	s_nop 0
	v_cndmask_b32_e32 v82, v183, v82, vcc
	v_cndmask_b32_e32 v83, v230, v83, vcc
	v_cmp_le_i32_e32 vcc, v182, v170
	v_add_u32_e32 v182, 0xffffff83, v181
	s_nop 0
	v_cndmask_b32_e32 v84, v230, v84, vcc
	v_cmp_le_i32_e32 vcc, v182, v170
	v_add_u32_e32 v182, 0xffffff88, v181
	s_nop 0
	v_cndmask_b32_e32 v85, v230, v85, vcc
	v_cmp_le_i32_e32 vcc, v182, v170
	v_add_u32_e32 v182, 0xffffff89, v181
	s_nop 0
	v_cndmask_b32_e32 v86, v230, v86, vcc
	v_cmp_le_i32_e32 vcc, v182, v170
	v_add_u32_e32 v182, 0xffffff8a, v181
	s_nop 0
	v_cndmask_b32_e32 v87, v230, v87, vcc
	v_cmp_le_i32_e32 vcc, v182, v170
	v_add_u32_e32 v182, 0xffffff8b, v181
	s_nop 0
	v_cndmask_b32_e32 v88, v230, v88, vcc
	v_cmp_le_i32_e32 vcc, v182, v170
	v_add_u32_e32 v182, 0xffffff90, v181
	s_nop 0
	v_cndmask_b32_e32 v89, v230, v89, vcc
	v_cmp_le_i32_e32 vcc, v182, v170
	v_add_u32_e32 v182, 0xffffff91, v181
	s_nop 0
	v_cndmask_b32_e32 v90, v230, v90, vcc
	v_cmp_le_i32_e32 vcc, v182, v170
	v_add_u32_e32 v182, 0xffffff92, v181
	s_nop 0
	v_cndmask_b32_e32 v91, v230, v91, vcc
	v_cmp_le_i32_e32 vcc, v182, v170
	v_add_u32_e32 v182, 0xffffff93, v181
	s_nop 0
	v_cndmask_b32_e32 v92, v230, v92, vcc
	v_cmp_le_i32_e32 vcc, v182, v170
	v_add_u32_e32 v182, 0xffffff98, v181
; template <int DQK, int KROW, bool BIAS, bool MAPS2>
; DI void attn_core(const int t, const u16* __restrict__ Q, int ldq, const u16* __restrict__ Kp, int ldk, const u16* __restrict__ Vt, int q0,
;                   char* lds, const float* lut, float b31, f32x16 (&o)[4], float& l_out) {
;     ...
;       if (k0 + 63 > wq0) {
; #pragma unroll
;         for (int k2 = 0; k2 < 2; ++k2)
; #pragma unroll
;           for (int i = 0; i < 16; ++i) {
;             const int key = k0 + 32 * k2 + (i & 3) + 8 * (i >> 2) + 4 * hf;
;             if (key > qrow) s[k2][i] = -INFINITY;
;           }
;       }
;       float mx = s[0][0];
; #pragma unroll
;       for (int k2 = 0; k2 < 2; ++k2)
; #pragma unroll
;         for (int i = 0; i < 16; ++i) mx = fmaxf(mx, s[k2][i]);
;       mx = xhalf_max(mx);
;       if (__builtin_amdgcn_ballot_w64(kt == 0 || mx > RESCALE_THR)) {
;         const float delta = (kt == 0) ? mx : fmaxf(mx, 0.f);
;         const float alpha = __builtin_amdgcn_exp2f(-delta);
;         m_run += delta;
;         l_run *= alpha;
; #pragma unroll
;         for (int dt = 0; dt < 4; ++dt)
; #pragma unroll
;           for (int i = 0; i < 16; ++i) o[dt][i] *= alpha;
; #pragma unroll
;         for (int k2 = 0; k2 < 2; ++k2)
; #pragma unroll
;           for (int i = 0; i < 16; ++i) s[k2][i] -= delta;
;       }
	s_nop 0
	v_cndmask_b32_e32 v93, v230, v93, vcc
	v_cmp_le_i32_e32 vcc, v182, v170
	v_add_u32_e32 v182, 0xffffff99, v181
	s_nop 0
	v_cndmask_b32_e32 v94, v230, v94, vcc
	v_cmp_le_i32_e32 vcc, v182, v170
	v_add_u32_e32 v182, 0xffffff9a, v181
	s_nop 0
	v_cndmask_b32_e32 v95, v230, v95, vcc
	v_cmp_le_i32_e32 vcc, v182, v170
	v_add_u32_e32 v182, 0xffffff9b, v181
	s_nop 0
	v_cndmask_b32_e32 v96, v230, v96, vcc
	v_cmp_le_i32_e32 vcc, v182, v170
	v_add_u32_e32 v182, 0xffffffa0, v181
	s_nop 0
	v_cndmask_b32_e32 v97, v230, v97, vcc
	v_cmp_le_i32_e32 vcc, v182, v170
	v_add_u32_e32 v182, 0xffffffa1, v181
	s_nop 0
	v_cndmask_b32_e32 v66, v230, v66, vcc
	v_cmp_le_i32_e32 vcc, v182, v170
	v_add_u32_e32 v182, 0xffffffa2, v181
	s_nop 0
	v_cndmask_b32_e32 v67, v230, v67, vcc
	v_cmp_le_i32_e32 vcc, v182, v170
	v_add_u32_e32 v182, 0xffffffa3, v181
	s_nop 0
	v_cndmask_b32_e32 v68, v230, v68, vcc
	v_cmp_le_i32_e32 vcc, v182, v170
	v_add_u32_e32 v182, 0xffffffa8, v181
	s_nop 0
	v_cndmask_b32_e32 v69, v230, v69, vcc
	v_cmp_le_i32_e32 vcc, v182, v170
	v_add_u32_e32 v182, 0xffffffa9, v181
	s_nop 0
	v_cndmask_b32_e32 v70, v230, v70, vcc
	v_cmp_le_i32_e32 vcc, v182, v170
	v_add_u32_e32 v182, 0xffffffaa, v181
	s_nop 0
	v_cndmask_b32_e32 v71, v230, v71, vcc
	v_cmp_le_i32_e32 vcc, v182, v170
	v_add_u32_e32 v182, 0xffffffab, v181
	s_nop 0
	v_cndmask_b32_e32 v72, v230, v72, vcc
	v_cmp_le_i32_e32 vcc, v182, v170
	v_add_u32_e32 v182, 0xffffffb0, v181
	s_nop 0
	v_cndmask_b32_e32 v73, v230, v73, vcc
	v_cmp_le_i32_e32 vcc, v182, v170
	v_add_u32_e32 v182, 0xffffffb1, v181
	s_nop 0
	v_cndmask_b32_e32 v74, v230, v74, vcc
	v_cmp_le_i32_e32 vcc, v182, v170
	v_add_u32_e32 v182, 0xffffffb2, v181
	s_nop 0
	v_cndmask_b32_e32 v75, v230, v75, vcc
	v_cmp_le_i32_e32 vcc, v182, v170
	v_add_u32_e32 v182, 0xffffffb3, v181
	s_nop 0
	v_cndmask_b32_e32 v76, v230, v76, vcc
	v_cmp_le_i32_e32 vcc, v182, v170
	v_add_u32_e32 v182, 0xffffffb8, v181
	s_nop 0
	v_cndmask_b32_e32 v77, v230, v77, vcc
	v_cmp_le_i32_e32 vcc, v182, v170
	v_add_u32_e32 v182, 0xffffffb9, v181
	s_nop 0
	v_cndmask_b32_e32 v78, v230, v78, vcc
	v_cmp_le_i32_e32 vcc, v182, v170
	v_add_u32_e32 v182, 0xffffffba, v181
	v_add_u32_e32 v181, 0xffffffbb, v181
	v_cndmask_b32_e32 v79, v230, v79, vcc
	v_cmp_le_i32_e32 vcc, v182, v170
	s_nop 1
	v_cndmask_b32_e32 v80, v230, v80, vcc
	v_cmp_le_i32_e32 vcc, v181, v170
	s_nop 1
	v_cndmask_b32_e32 v81, v230, v81, vcc
.LBB0_273:
	s_or_b64 exec, exec, s[0:1]
	s_nop 3
	v_max_f32_e32 v181, v83, v83
	v_max_f32_e32 v182, v82, v82
	v_max_f32_e32 v181, v182, v181
	v_max3_f32 v181, v181, v84, v85
	v_max3_f32 v181, v181, v86, v87
	v_max3_f32 v181, v181, v88, v89
	v_max3_f32 v181, v181, v90, v91
	v_max3_f32 v181, v181, v92, v93
	v_max3_f32 v181, v181, v94, v95
	v_max3_f32 v181, v181, v96, v97
	v_max3_f32 v181, v181, v66, v67
	v_max3_f32 v181, v181, v68, v69
	v_max3_f32 v181, v181, v70, v71
	v_max3_f32 v181, v181, v72, v73
	v_max3_f32 v181, v181, v74, v75
	v_max3_f32 v181, v181, v76, v77
	v_max3_f32 v181, v181, v78, v79
	v_max3_f32 v181, v181, v80, v81
	v_mov_b32_e32 v182, v181
	s_nop 1
	v_permlane32_swap_b32_e32 v181, v182
	v_max_f32_e32 v181, v181, v182
	v_cmp_lt_f32_e32 vcc, s97, v181
	s_cbranch_vccz .LBB0_275
	s_cmp_eq_u32 s63, 0
	s_cselect_b64 s[0:1], -1, 0
	v_max_f32_e32 v182, v181, v181
	v_max_f32_e32 v182, 0, v182
	v_cndmask_b32_e64 v182, v182, v181, s[0:1]
	v_exp_f32_e64 v184, -v182
	v_add_f32_e32 v180, v180, v182
	v_pk_add_f32 v[82:83], v[82:83], v[182:183] op_sel_hi:[1,0] neg_lo:[0,1] neg_hi:[0,1]
	v_pk_add_f32 v[84:85], v[84:85], v[182:183] op_sel_hi:[1,0] neg_lo:[0,1] neg_hi:[0,1]
	v_pk_mul_f32 v[64:65], v[64:65], v[184:185] op_sel_hi:[1,0]
	v_pk_mul_f32 v[62:63], v[62:63], v[184:185] op_sel_hi:[1,0]
	v_pk_mul_f32 v[60:61], v[60:61], v[184:185] op_sel_hi:[1,0]
	v_pk_mul_f32 v[58:59], v[58:59], v[184:185] op_sel_hi:[1,0]
	v_pk_mul_f32 v[56:57], v[56:57], v[184:185] op_sel_hi:[1,0]
	v_pk_mul_f32 v[54:55], v[54:55], v[184:185] op_sel_hi:[1,0]
	v_pk_mul_f32 v[52:53], v[52:53], v[184:185] op_sel_hi:[1,0]
	v_pk_mul_f32 v[50:51], v[50:51], v[184:185] op_sel_hi:[1,0]
	v_pk_mul_f32 v[48:49], v[48:49], v[184:185] op_sel_hi:[1,0]
	v_pk_mul_f32 v[46:47], v[46:47], v[184:185] op_sel_hi:[1,0]
	v_pk_mul_f32 v[44:45], v[44:45], v[184:185] op_sel_hi:[1,0]
	v_pk_mul_f32 v[42:43], v[42:43], v[184:185] op_sel_hi:[1,0]
	v_pk_mul_f32 v[40:41], v[40:41], v[184:185] op_sel_hi:[1,0]
	v_pk_mul_f32 v[38:39], v[38:39], v[184:185] op_sel_hi:[1,0]
	v_pk_mul_f32 v[36:37], v[36:37], v[184:185] op_sel_hi:[1,0]
	v_pk_mul_f32 v[34:35], v[34:35], v[184:185] op_sel_hi:[1,0]
	v_pk_mul_f32 v[32:33], v[32:33], v[184:185] op_sel_hi:[1,0]
	v_pk_mul_f32 v[30:31], v[30:31], v[184:185] op_sel_hi:[1,0]
	v_pk_mul_f32 v[28:29], v[28:29], v[184:185] op_sel_hi:[1,0]
	v_pk_mul_f32 v[26:27], v[26:27], v[184:185] op_sel_hi:[1,0]
	v_pk_mul_f32 v[24:25], v[24:25], v[184:185] op_sel_hi:[1,0]
	v_pk_mul_f32 v[22:23], v[22:23], v[184:185] op_sel_hi:[1,0]
	v_pk_mul_f32 v[20:21], v[20:21], v[184:185] op_sel_hi:[1,0]
	v_pk_mul_f32 v[18:19], v[18:19], v[184:185] op_sel_hi:[1,0]
	v_pk_mul_f32 v[16:17], v[16:17], v[184:185] op_sel_hi:[1,0]
	v_pk_mul_f32 v[14:15], v[14:15], v[184:185] op_sel_hi:[1,0]
	v_pk_mul_f32 v[12:13], v[12:13], v[184:185] op_sel_hi:[1,0]
	v_pk_mul_f32 v[10:11], v[10:11], v[184:185] op_sel_hi:[1,0]
	v_pk_mul_f32 v[8:9], v[8:9], v[184:185] op_sel_hi:[1,0]
	v_pk_mul_f32 v[6:7], v[6:7], v[184:185] op_sel_hi:[1,0]
	v_pk_mul_f32 v[4:5], v[4:5], v[184:185] op_sel_hi:[1,0]
	v_pk_mul_f32 v[2:3], v[2:3], v[184:185] op_sel_hi:[1,0]
	v_pk_add_f32 v[86:87], v[86:87], v[182:183] op_sel_hi:[1,0] neg_lo:[0,1] neg_hi:[0,1]
	v_pk_add_f32 v[88:89], v[88:89], v[182:183] op_sel_hi:[1,0] neg_lo:[0,1] neg_hi:[0,1]
	v_pk_add_f32 v[90:91], v[90:91], v[182:183] op_sel_hi:[1,0] neg_lo:[0,1] neg_hi:[0,1]
	v_pk_add_f32 v[92:93], v[92:93], v[182:183] op_sel_hi:[1,0] neg_lo:[0,1] neg_hi:[0,1]
	v_pk_add_f32 v[94:95], v[94:95], v[182:183] op_sel_hi:[1,0] neg_lo:[0,1] neg_hi:[0,1]
	v_pk_add_f32 v[96:97], v[96:97], v[182:183] op_sel_hi:[1,0] neg_lo:[0,1] neg_hi:[0,1]
	v_pk_add_f32 v[66:67], v[66:67], v[182:183] op_sel_hi:[1,0] neg_lo:[0,1] neg_hi:[0,1]
	v_pk_add_f32 v[68:69], v[68:69], v[182:183] op_sel_hi:[1,0] neg_lo:[0,1] neg_hi:[0,1]
	v_pk_add_f32 v[70:71], v[70:71], v[182:183] op_sel_hi:[1,0] neg_lo:[0,1] neg_hi:[0,1]
	v_pk_add_f32 v[72:73], v[72:73], v[182:183] op_sel_hi:[1,0] neg_lo:[0,1] neg_hi:[0,1]
	v_pk_add_f32 v[74:75], v[74:75], v[182:183] op_sel_hi:[1,0] neg_lo:[0,1] neg_hi:[0,1]
	v_pk_add_f32 v[76:77], v[76:77], v[182:183] op_sel_hi:[1,0] neg_lo:[0,1] neg_hi:[0,1]
	v_pk_add_f32 v[78:79], v[78:79], v[182:183] op_sel_hi:[1,0] neg_lo:[0,1] neg_hi:[0,1]
	v_pk_add_f32 v[80:81], v[80:81], v[182:183] op_sel_hi:[1,0] neg_lo:[0,1] neg_hi:[0,1]
	v_mul_f32_e32 v0, v0, v184
